# K-fragment prefetch reads moved two MFMA gaps earlier in both attention loops so the pre-barrier lgkmcnt(0) no longer waits on fresh reads
# speedup vs baseline: 1.0008x; 1.0008x over previous
; template <int DK, int PAR, bool HASNEXT, bool LDK, bool LDV, bool STK> ...
;     ...
;             kf[ds][0] = *(const LAS bf16x8*)(Kb + aoffk + ds * 32);
;             kf[ds][1] = *(const LAS bf16x8*)(Kb + aoffk + 32 * A::KSTR + ds * 32);
;         }
;     }
;     s16x4 vlo[4][2], vhi[4][2];
; #pragma unroll
;     for (int j = 0; j < 2; ++j) {
;         vlo[j][0] = vtr(Vb + aoffv + j * 16 * A::VSTR); vhi[j][0] = vtr(Vb + aoffv + (j * 16 + 8) * A::VSTR);
;         vlo[j][1] = vtr(Vb + aoffv + j * 16 * A::VSTR + 64); vhi[j][1] = vtr(Vb + aoffv + (j * 16 + 8) * A::VSTR + 64);
;     }
;     if (HASNEXT) {
;         f32x16 z;
; #pragma unroll
;         for (int i = 0; i < 16; ++i) z[i] = 0.f;
; #pragma unroll
;         for (int ds = 0; ds < A::NDS; ++ds) {
;             N0 = __builtin_amdgcn_mfma_f32_32x32x16_bf16(kf[ds][0], qf[ds], ds == 0 ? z : N0, 0, 0, 0);
;             N1 = __builtin_amdgcn_mfma_f32_32x32x16_bf16(kf[ds][1], qf[ds], ds == 0 ? z : N1, 0, 0, 0);
;         }
;     }
; #pragma unroll
;     for (int i = 0; i < 16; ++i) { l += C0[i]; l += C1[i]; }
;     bf16x8 pb[4];
;     { u32x4 w;
;       w.x = pk2(C0[0], C0[1]); w.y = pk2(C0[2], C0[3]); w.z = pk2(C0[4], C0[5]); w.w = pk2(C0[6], C0[7]); pb[0] = __builtin_bit_cast(bf16x8, w);
;       w.x = pk2(C0[8], C0[9]); w.y = pk2(C0[10], C0[11]); w.z = pk2(C0[12], C0[13]); w.w = pk2(C0[14], C0[15]); pb[1] = __builtin_bit_cast(bf16x8, w);
;       w.x = pk2(C1[0], C1[1]); w.y = pk2(C1[2], C1[3]); w.z = pk2(C1[4], C1[5]); w.w = pk2(C1[6], C1[7]); pb[2] = __builtin_bit_cast(bf16x8, w);
;       w.x = pk2(C1[8], C1[9]); w.y = pk2(C1[10], C1[11]); w.z = pk2(C1[12], C1[13]); w.w = pk2(C1[14], C1[15]); pb[3] = __builtin_bit_cast(bf16x8, w); }
;     if (HASNEXT) {
;         constexpr int VPER = (DK == 64) ? 6 : 4;
; #pragma unroll
;         for (int g = 0; g < 2 * A::NDS; ++g) { __builtin_amdgcn_sched_group_barrier(0x008, 1, 0); __builtin_amdgcn_sched_group_barrier(0x002, VPER, 0); }
;     }
;     asm volatile("" : "+v"(l));
;     __builtin_amdgcn_sched_barrier(0);
; #pragma unroll
;     for (int j = 2; j < 4; ++j) {
;         vlo[j][0] = vtr(Vb + aoffv + j * 16 * A::VSTR); vhi[j][0] = vtr(Vb + aoffv + (j * 16 + 8) * A::VSTR);
;         vlo[j][1] = vtr(Vb + aoffv + j * 16 * A::VSTR + 64); vhi[j][1] = vtr(Vb + aoffv + (j * 16 + 8) * A::VSTR + 64);
;     }
; #pragma unroll
;     for (int j = 0; j < 4; ++j) {
.LBB0_765:
	s_or_b64 exec, exec, s[10:11]
	ds_read_b64_tr_b16 v[204:205], v172 offset:26624
	ds_read_b64_tr_b16 v[206:207], v172 offset:28160
	ds_read_b64_tr_b16 v[212:213], v172 offset:29696
	ds_read_b64_tr_b16 v[214:215], v172 offset:31232
	v_lshl_add_u64 v[80:81], s[50:51], 0, v[168:169]
	v_add_co_u32_e32 v94, vcc, 0x14f30000, v80
	v_add_f32_e32 v96, v185, v48
	s_nop 0
	v_addc_co_u32_e32 v95, vcc, 0, v81, vcc
	global_load_dwordx4 v[144:147], v[94:95], off offset:128
	v_mfma_f32_32x32x16_bf16 v[48:63], v[220:223], v[120:123], 0
	v_add_f32_e32 v96, v183, v96
	v_add_f32_e32 v96, v187, v96
	v_add_f32_e32 v96, v184, v96
	v_add_f32_e32 v96, v186, v96
	v_mfma_f32_32x32x16_bf16 v[32:47], v[224:227], v[116:119], v[32:47]
	v_add_f32_e32 v96, v82, v96
	v_add_f32_e32 v96, v189, v96
	v_add_f32_e32 v96, v83, v96
	v_add_f32_e32 v96, v188, v96
	v_mfma_f32_32x32x16_bf16 v[48:63], v[228:231], v[116:119], v[48:63]
	s_waitcnt vmcnt(3)
	ds_write_b128 v173, v[132:135] offset:13312
	s_and_saveexec_b64 s[10:11], s[6:7]
	ds_write_b128 v182, v[128:131] offset:13312
	s_or_b64 exec, exec, s[10:11]
	s_waitcnt vmcnt(2)
	ds_write_b128 v170, v[136:139] offset:38912
	v_add_f32_e32 v94, v84, v96
	v_add_f32_e32 v94, v190, v94
	v_add_f32_e32 v94, v85, v94
	v_add_f32_e32 v94, v192, v94
	v_mfma_f32_32x32x16_bf16 v[32:47], v[236:239], v[112:115], v[32:47]
	v_add_f32_e32 v94, v86, v94
	v_add_f32_e32 v94, v194, v94
	v_add_f32_e32 v94, v87, v94
	v_add_f32_e32 v94, v191, v94
	v_mfma_f32_32x32x16_bf16 v[48:63], v[240:243], v[112:115], v[48:63]
	v_add_f32_e32 v94, v72, v94
	v_add_f32_e32 v94, v193, v94
	v_add_f32_e32 v94, v73, v94
	v_add_f32_e32 v94, v88, v94
	v_mfma_f32_32x32x16_bf16 v[32:47], v[244:247], v[108:111], v[32:47]
	v_add_f32_e32 v94, v74, v94
	v_add_f32_e32 v94, v90, v94
	v_add_f32_e32 v94, v75, v94
	v_add_f32_e32 v94, v89, v94
	v_mfma_f32_32x32x16_bf16 v[48:63], v[248:251], v[108:111], v[48:63]
	v_add_f32_e32 v94, v76, v94
	v_add_f32_e32 v94, v91, v94
	v_add_f32_e32 v94, v77, v94
	v_add_f32_e32 v94, v92, v94
	v_mfma_f32_32x32x16_bf16 v[32:47], v[68:71], v[104:107], v[32:47]
	v_add_f32_e32 v94, v78, v94
	v_add_f32_e32 v94, v93, v94
	v_add_f32_e32 v94, v79, v94
	v_cvt_pk_bf16_f32 v216, v185, v187
	v_mfma_f32_32x32x16_bf16 v[48:63], v[196:199], v[104:107], v[48:63]
	v_cvt_pk_bf16_f32 v217, v186, v189
	v_cvt_pk_bf16_f32 v218, v188, v190
	v_cvt_pk_bf16_f32 v219, v192, v194
	v_cvt_pk_bf16_f32 v186, v191, v193
	ds_read_b64_tr_b16 v[196:197], v172 offset:26688
	ds_read_b64_tr_b16 v[198:199], v172 offset:28224
	ds_read_b64_tr_b16 v[190:191], v172 offset:29760
	v_mfma_f32_32x32x16_bf16 v[32:47], v[200:203], v[100:103], v[32:47]
	v_cvt_pk_bf16_f32 v187, v88, v90
	v_cvt_pk_bf16_f32 v188, v89, v91
	v_cvt_pk_bf16_f32 v189, v92, v93
	v_cvt_pk_bf16_f32 v88, v183, v184
	ds_read_b64_tr_b16 v[192:193], v172 offset:31296
	v_mfma_f32_32x32x16_bf16 v[48:63], v[208:211], v[100:103], v[48:63]
	v_cvt_pk_bf16_f32 v89, v82, v83
	v_cvt_pk_bf16_f32 v90, v84, v85
	v_cvt_pk_bf16_f32 v91, v86, v87
	v_cvt_pk_bf16_f32 v68, v72, v73
	v_cvt_pk_bf16_f32 v69, v74, v75
	v_cvt_pk_bf16_f32 v70, v76, v77
	v_cvt_pk_bf16_f32 v71, v78, v79
	s_waitcnt lgkmcnt(9)
	v_mfma_f32_32x32x16_bf16 v[16:31], v[204:207], v[216:219], v[16:31]
	ds_read_b64_tr_b16 v[72:73], v172 offset:32768
	ds_read_b64_tr_b16 v[74:75], v172 offset:34304
	ds_read_b64_tr_b16 v[76:77], v172 offset:32832
	ds_read_b64_tr_b16 v[78:79], v172 offset:34368
	v_exp_f32_e32 v96, v32
	v_exp_f32_e32 v99, v33
	v_exp_f32_e32 v150, v34
	s_waitcnt lgkmcnt(6)
	v_mfma_f32_32x32x16_bf16 v[0:15], v[196:199], v[216:219], v[0:15]
	ds_read_b128 v[220:223], v181 offset:6656
	ds_read_b128 v[224:227], v181 offset:32
	ds_read_b128 v[228:231], v181 offset:6688
	v_exp_f32_e32 v152, v35
	v_exp_f32_e32 v154, v36
	v_exp_f32_e32 v184, v39
	v_mfma_f32_32x32x16_bf16 v[16:31], v[212:215], v[186:189], v[16:31]
	ds_read_b128 v[216:219], v181
	ds_read_b128 v[236:239], v181 offset:64
	ds_read_b128 v[240:243], v181 offset:6720
	v_exp_f32_e32 v185, v40
	v_exp_f32_e32 v155, v52
	v_exp_f32_e32 v52, v37
	s_waitcnt lgkmcnt(10)
	v_mfma_f32_32x32x16_bf16 v[0:15], v[190:193], v[186:189], v[0:15]
	ds_read_b128 v[244:247], v181 offset:96
	ds_read_b128 v[248:251], v181 offset:6752
	ds_read_b128 v[32:35], v181 offset:128
	v_exp_f32_e32 v180, v53
	v_exp_f32_e32 v53, v38
	v_exp_f32_e32 v98, v48
	s_waitcnt lgkmcnt(11)
	v_mfma_f32_32x32x16_bf16 v[16:31], v[72:75], v[88:91], v[16:31]
	ds_read_b64_tr_b16 v[72:73], v172 offset:35840
	ds_read_b64_tr_b16 v[74:75], v172 offset:37376
	ds_read_b128 v[196:199], v181 offset:160
	s_waitcnt lgkmcnt(13)
	ds_read_b128 v[200:203], v181 offset:6816
	s_waitcnt lgkmcnt(13)
	ds_read_b128 v[36:39], v181 offset:6784
	v_exp_f32_e32 v49, v49
	v_exp_f32_e32 v151, v50
	v_exp_f32_e32 v153, v51
	v_mfma_f32_32x32x16_bf16 v[0:15], v[76:79], v[88:91], v[0:15]
	s_waitcnt lgkmcnt(13)
	ds_read_b64_tr_b16 v[76:77], v172 offset:35904
	s_waitcnt lgkmcnt(13)
	ds_read_b64_tr_b16 v[78:79], v172 offset:37440
	v_exp_f32_e32 v183, v54
	v_exp_f32_e32 v187, v55
	s_waitcnt lgkmcnt(5)
	v_mfma_f32_32x32x16_bf16 v[16:31], v[72:75], v[68:71], v[16:31]
	v_exp_f32_e32 v188, v56
	v_exp_f32_e32 v56, v41
	s_waitcnt lgkmcnt(0)
	v_mfma_f32_32x32x16_bf16 v[0:15], v[76:79], v[68:71], v[0:15]
	v_exp_f32_e32 v189, v57
	s_setprio 0
	s_waitcnt lgkmcnt(0)
	s_barrier
	s_setprio 1
	v_add_co_u32_e32 v66, vcc, 0x2a5ba000, v66
	s_nop 1
	v_addc_co_u32_e32 v67, vcc, 0, v67, vcc
	global_load_dwordx4 v[132:135], v[66:67], off
	s_and_saveexec_b64 s[10:11], s[6:7]
	s_cbranch_execz .LBB0_769
	v_add_co_u32_e32 v64, vcc, 0x2a5ba000, v64
	s_nop 1
	v_addc_co_u32_e32 v65, vcc, 0, v65, vcc
	global_load_dwordx4 v[128:131], v[64:65], off
; template <int DK, int PAR, bool HASNEXT, bool LDK, bool LDV, bool STK> ...
;     ...
; #pragma unroll
;         for (int ds = 0; ds < A::NDS; ++ds) {
;             kf[ds][0] = *(const LAS bf16x8*)(Kb + aoffk + ds * 32);
;             kf[ds][1] = *(const LAS bf16x8*)(Kb + aoffk + 32 * A::KSTR + ds * 32);
;         }
;     }
;     s16x4 vlo[4][2], vhi[4][2];
; #pragma unroll
;     for (int j = 0; j < 2; ++j) {
;         vlo[j][0] = vtr(Vb + aoffv + j * 16 * A::VSTR); vhi[j][0] = vtr(Vb + aoffv + (j * 16 + 8) * A::VSTR);
;         vlo[j][1] = vtr(Vb + aoffv + j * 16 * A::VSTR + 64); vhi[j][1] = vtr(Vb + aoffv + (j * 16 + 8) * A::VSTR + 64);
;     }
;     if (HASNEXT) {
;         f32x16 z;
; #pragma unroll
;         for (int i = 0; i < 16; ++i) z[i] = 0.f;
; #pragma unroll
;         for (int ds = 0; ds < A::NDS; ++ds) {
;             N0 = __builtin_amdgcn_mfma_f32_32x32x16_bf16(kf[ds][0], qf[ds], ds == 0 ? z : N0, 0, 0, 0);
;             N1 = __builtin_amdgcn_mfma_f32_32x32x16_bf16(kf[ds][1], qf[ds], ds == 0 ? z : N1, 0, 0, 0);
;         }
;     }
; #pragma unroll
;     for (int i = 0; i < 16; ++i) { l += C0[i]; l += C1[i]; }
;     bf16x8 pb[4];
;     { u32x4 w;
;       w.x = pk2(C0[0], C0[1]); w.y = pk2(C0[2], C0[3]); w.z = pk2(C0[4], C0[5]); w.w = pk2(C0[6], C0[7]); pb[0] = __builtin_bit_cast(bf16x8, w);
;       w.x = pk2(C0[8], C0[9]); w.y = pk2(C0[10], C0[11]); w.z = pk2(C0[12], C0[13]); w.w = pk2(C0[14], C0[15]); pb[1] = __builtin_bit_cast(bf16x8, w);
;       w.x = pk2(C1[0], C1[1]); w.y = pk2(C1[2], C1[3]); w.z = pk2(C1[4], C1[5]); w.w = pk2(C1[6], C1[7]); pb[2] = __builtin_bit_cast(bf16x8, w);
;       w.x = pk2(C1[8], C1[9]); w.y = pk2(C1[10], C1[11]); w.z = pk2(C1[12], C1[13]); w.w = pk2(C1[14], C1[15]); pb[3] = __builtin_bit_cast(bf16x8, w); }
;     if (HASNEXT) {
;         constexpr int VPER = (DK == 64) ? 6 : 4;
; #pragma unroll
;         for (int g = 0; g < 2 * A::NDS; ++g) { __builtin_amdgcn_sched_group_barrier(0x008, 1, 0); __builtin_amdgcn_sched_group_barrier(0x002, VPER, 0); }
;     }
;     asm volatile("" : "+v"(l));
;     __builtin_amdgcn_sched_barrier(0);
; #pragma unroll
;     for (int j = 2; j < 4; ++j) {
;         vlo[j][0] = vtr(Vb + aoffv + j * 16 * A::VSTR); vhi[j][0] = vtr(Vb + aoffv + (j * 16 + 8) * A::VSTR);
;         vlo[j][1] = vtr(Vb + aoffv + j * 16 * A::VSTR + 64); vhi[j][1] = vtr(Vb + aoffv + (j * 16 + 8) * A::VSTR + 64);
;     }
.LBB0_769:
	s_or_b64 exec, exec, s[10:11]
	s_mov_b32 s10, 0x14f48000
	v_mfma_f32_32x32x16_bf16 v[64:79], v[216:219], v[120:123], 0
	v_exp_f32_e32 v57, v42
	v_exp_f32_e32 v190, v58
	v_add_co_u32_e32 v40, vcc, s10, v80
	s_nop 0
	v_addc_co_u32_e32 v41, vcc, 0, v81, vcc
	global_load_dwordx4 v[136:139], v[40:41], off offset:128
	v_add_f32_e32 v48, v96, v94
	v_add_f32_e32 v48, v98, v48
	v_mfma_f32_32x32x16_bf16 v[80:95], v[220:223], v[120:123], 0
	v_exp_f32_e32 v186, v43
	v_exp_f32_e32 v191, v59
	v_add_f32_e32 v40, v99, v48
	v_add_f32_e32 v40, v49, v40
	v_add_f32_e32 v40, v150, v40
	v_add_f32_e32 v40, v151, v40
	v_mfma_f32_32x32x16_bf16 v[64:79], v[224:227], v[116:119], v[64:79]
	v_exp_f32_e32 v192, v44
	v_exp_f32_e32 v193, v60
	v_add_f32_e32 v40, v152, v40
	v_add_f32_e32 v40, v153, v40
	v_add_f32_e32 v40, v154, v40
	v_add_f32_e32 v40, v155, v40
	v_mfma_f32_32x32x16_bf16 v[80:95], v[228:231], v[116:119], v[80:95]
	v_exp_f32_e32 v60, v45
	v_exp_f32_e32 v194, v61
	s_waitcnt vmcnt(3)
	ds_write_b128 v173, v[140:143]
	s_and_saveexec_b64 s[10:11], s[6:7]
	ds_write_b128 v182, v[124:127]
	s_or_b64 exec, exec, s[10:11]
	s_waitcnt vmcnt(2)
	ds_write_b128 v170, v[144:147] offset:26624
	v_add_f32_e32 v40, v52, v40
	v_add_f32_e32 v40, v180, v40
	v_add_f32_e32 v40, v53, v40
	v_add_f32_e32 v40, v183, v40
	v_mfma_f32_32x32x16_bf16 v[64:79], v[236:239], v[112:115], v[64:79]
	v_exp_f32_e32 v61, v46
	v_exp_f32_e32 v62, v62
	v_add_f32_e32 v40, v184, v40
	v_add_f32_e32 v40, v187, v40
	v_add_f32_e32 v40, v185, v40
	v_add_f32_e32 v40, v188, v40
	v_mfma_f32_32x32x16_bf16 v[80:95], v[240:243], v[112:115], v[80:95]
	v_exp_f32_e32 v195, v47
	v_exp_f32_e32 v63, v63
	v_add_f32_e32 v40, v56, v40
	v_add_f32_e32 v40, v189, v40
	v_add_f32_e32 v40, v57, v40
	v_add_f32_e32 v40, v190, v40
	v_mfma_f32_32x32x16_bf16 v[64:79], v[244:247], v[108:111], v[64:79]
	v_add_f32_e32 v40, v186, v40
	v_add_f32_e32 v40, v191, v40
	v_add_f32_e32 v40, v192, v40
	v_add_f32_e32 v44, v193, v40
	v_mfma_f32_32x32x16_bf16 v[80:95], v[248:251], v[108:111], v[80:95]
	v_add_f32_e32 v44, v60, v44
	v_add_f32_e32 v44, v194, v44
	v_add_f32_e32 v44, v61, v44
	v_add_f32_e32 v48, v62, v44
	v_mfma_f32_32x32x16_bf16 v[64:79], v[32:35], v[104:107], v[64:79]
	v_add_f32_e32 v48, v195, v48
	v_add_f32_e32 v48, v63, v48
	v_cvt_pk_bf16_f32 v50, v96, v99
	v_cvt_pk_bf16_f32 v51, v150, v152
	ds_read_b64_tr_b16 v[44:45], v172 offset:38912
	ds_read_b64_tr_b16 v[46:47], v172 offset:40448
	v_mfma_f32_32x32x16_bf16 v[80:95], v[36:39], v[104:107], v[80:95]
	v_cvt_pk_bf16_f32 v52, v154, v52
	v_cvt_pk_bf16_f32 v53, v53, v184
	v_cvt_pk_bf16_f32 v58, v185, v56
	v_cvt_pk_bf16_f32 v59, v57, v186
	ds_read_b64_tr_b16 v[36:37], v172 offset:38976
	ds_read_b64_tr_b16 v[38:39], v172 offset:40512
	ds_read_b64_tr_b16 v[54:55], v172 offset:41984
	v_mfma_f32_32x32x16_bf16 v[64:79], v[196:199], v[100:103], v[64:79]
	v_cvt_pk_bf16_f32 v60, v192, v60
	v_cvt_pk_bf16_f32 v61, v61, v195
	v_cvt_pk_bf16_f32 v184, v98, v49
	v_cvt_pk_bf16_f32 v185, v151, v153
	ds_read_b64_tr_b16 v[56:57], v172 offset:43520
	ds_read_b64_tr_b16 v[40:41], v172 offset:42048
	ds_read_b64_tr_b16 v[42:43], v172 offset:43584
	v_mfma_f32_32x32x16_bf16 v[80:95], v[200:203], v[100:103], v[80:95]
	v_cvt_pk_bf16_f32 v186, v155, v180
	v_cvt_pk_bf16_f32 v187, v183, v187
	v_cvt_pk_bf16_f32 v32, v188, v189
	v_cvt_pk_bf16_f32 v33, v190, v191
	v_cvt_pk_bf16_f32 v34, v193, v194
	v_cvt_pk_bf16_f32 v35, v62, v63
	s_waitcnt lgkmcnt(6)
	v_mfma_f32_32x32x16_bf16 v[16:31], v[44:47], v[50:53], v[16:31]
	v_exp_f32_e32 v189, v67
	v_exp_f32_e32 v188, v68
	v_exp_f32_e32 v190, v69
	v_exp_f32_e32 v192, v70
	s_waitcnt lgkmcnt(4)
	v_mfma_f32_32x32x16_bf16 v[0:15], v[36:39], v[50:53], v[0:15]
	ds_read_b64_tr_b16 v[36:37], v172 offset:45056
	ds_read_b64_tr_b16 v[38:39], v172 offset:46592
	ds_read_b128 v[216:219], v181 offset:13312
	ds_read_b128 v[220:223], v181 offset:19968
	ds_read_b128 v[224:227], v181 offset:13344
	v_exp_f32_e32 v194, v71
	v_exp_f32_e32 v191, v72
	v_exp_f32_e32 v193, v73
	v_exp_f32_e32 v183, v80
	s_waitcnt lgkmcnt(7)
	v_mfma_f32_32x32x16_bf16 v[16:31], v[54:57], v[58:61], v[16:31]
	ds_read_b128 v[228:231], v181 offset:20000
	ds_read_b128 v[236:239], v181 offset:13376
	ds_read_b128 v[240:243], v181 offset:20032
	v_exp_f32_e32 v82, v82
	v_exp_f32_e32 v83, v83
	v_exp_f32_e32 v84, v84
	v_exp_f32_e32 v85, v85
	s_waitcnt lgkmcnt(8)
	v_mfma_f32_32x32x16_bf16 v[0:15], v[40:43], v[58:61], v[0:15]
	ds_read_b64_tr_b16 v[40:41], v172 offset:45120
	ds_read_b64_tr_b16 v[42:43], v172 offset:46656
	ds_read_b128 v[244:247], v181 offset:13408
	ds_read_b128 v[248:251], v181 offset:20064
	ds_read_b128 v[68:71], v181 offset:13440
	v_exp_f32_e32 v86, v86
	v_exp_f32_e32 v87, v87
	v_exp_f32_e32 v72, v88
	v_exp_f32_e32 v73, v89
	s_waitcnt lgkmcnt(11)
	v_mfma_f32_32x32x16_bf16 v[16:31], v[36:39], v[184:187], v[16:31]
	ds_read_b64_tr_b16 v[36:37], v172 offset:48128
	ds_read_b64_tr_b16 v[38:39], v172 offset:49664
	ds_read_b128 v[196:199], v181 offset:20096
	s_waitcnt lgkmcnt(13)
	ds_read_b128 v[200:203], v181 offset:13472
	s_waitcnt lgkmcnt(13)
	ds_read_b128 v[208:211], v181 offset:20128
	v_exp_f32_e32 v88, v74
	v_exp_f32_e32 v74, v90
	v_exp_f32_e32 v90, v75
	v_exp_f32_e32 v75, v91
	s_waitcnt lgkmcnt(8)
	v_mfma_f32_32x32x16_bf16 v[0:15], v[40:43], v[184:187], v[0:15]
	ds_read_b64_tr_b16 v[40:41], v172 offset:48192
	ds_read_b64_tr_b16 v[42:43], v172 offset:49728
	v_exp_f32_e32 v89, v76
	v_exp_f32_e32 v76, v92
	v_exp_f32_e32 v91, v77
	v_exp_f32_e32 v77, v93
	s_waitcnt lgkmcnt(5)
	v_mfma_f32_32x32x16_bf16 v[16:31], v[36:39], v[32:35], v[16:31]
	v_exp_f32_e32 v92, v78
	v_exp_f32_e32 v78, v94
	v_exp_f32_e32 v93, v79
	v_exp_f32_e32 v79, v95
	s_waitcnt lgkmcnt(0)
	v_mfma_f32_32x32x16_bf16 v[0:15], v[40:43], v[32:35], v[0:15]
	v_exp_f32_e32 v185, v64
	v_exp_f32_e32 v187, v65
	v_exp_f32_e32 v184, v81
	v_exp_f32_e32 v186, v66
	s_setprio 0
	s_waitcnt lgkmcnt(0)
	s_barrier
	s_add_i32 s12, s12, 2
	s_mov_b64 s[10:11], 0x30000
	v_lshl_add_u64 v[164:165], v[164:165], 0, s[72:73]
	v_lshl_add_u64 v[166:167], v[166:167], 0, s[72:73]
	s_cmpk_lt_u32 s12, 0x7e
	v_lshl_add_u64 v[168:169], v[168:169], 0, s[10:11]
	s_cbranch_scc1 .LBB0_763
	s_branch .LBB0_781

; template <int DK, int PAR, bool HASNEXT, bool LDK, bool LDV, bool STK> ...
;     ...
;     if (LDK) { ldk0 = *(const u32x4*)(kg0 + (size_t)(t + 3) * kstep); if (has1) ldk1 = *(const u32x4*)(kg1 + (size_t)(t + 3) * kstep); }
;     if (LDV) ldv = *(const u32x4*)(vg + (size_t)(t + 2) * vstep);
;     bf16x8 kf[A::NDS][2];
;     if (HASNEXT) {
; #pragma unroll
;         for (int ds = 0; ds < A::NDS; ++ds) {
;             kf[ds][0] = *(const LAS bf16x8*)(Kb + aoffk + ds * 32);
;             kf[ds][1] = *(const LAS bf16x8*)(Kb + aoffk + 32 * A::KSTR + ds * 32);
;         }
;     }
;     s16x4 vlo[4][2], vhi[4][2];
; #pragma unroll
;     for (int j = 0; j < 2; ++j) {
;         vlo[j][0] = vtr(Vb + aoffv + j * 16 * A::VSTR); vhi[j][0] = vtr(Vb + aoffv + (j * 16 + 8) * A::VSTR);
;         vlo[j][1] = vtr(Vb + aoffv + j * 16 * A::VSTR + 64); vhi[j][1] = vtr(Vb + aoffv + (j * 16 + 8) * A::VSTR + 64);
;     }
;     if (HASNEXT) {
;         f32x16 z;
; #pragma unroll
;         for (int i = 0; i < 16; ++i) z[i] = 0.f;
; #pragma unroll
;         for (int ds = 0; ds < A::NDS; ++ds) {
;             N0 = __builtin_amdgcn_mfma_f32_32x32x16_bf16(kf[ds][0], qf[ds], ds == 0 ? z : N0, 0, 0, 0);
;             N1 = __builtin_amdgcn_mfma_f32_32x32x16_bf16(kf[ds][1], qf[ds], ds == 0 ? z : N1, 0, 0, 0);
;         }
;     }
; #pragma unroll
;     for (int i = 0; i < 16; ++i) { l += C0[i]; l += C1[i]; }
;     bf16x8 pb[4];
;     { u32x4 w;
;       w.x = pk2(C0[0], C0[1]); w.y = pk2(C0[2], C0[3]); w.z = pk2(C0[4], C0[5]); w.w = pk2(C0[6], C0[7]); pb[0] = __builtin_bit_cast(bf16x8, w);
;       w.x = pk2(C0[8], C0[9]); w.y = pk2(C0[10], C0[11]); w.z = pk2(C0[12], C0[13]); w.w = pk2(C0[14], C0[15]); pb[1] = __builtin_bit_cast(bf16x8, w);
;       w.x = pk2(C1[0], C1[1]); w.y = pk2(C1[2], C1[3]); w.z = pk2(C1[4], C1[5]); w.w = pk2(C1[6], C1[7]); pb[2] = __builtin_bit_cast(bf16x8, w);
;       w.x = pk2(C1[8], C1[9]); w.y = pk2(C1[10], C1[11]); w.z = pk2(C1[12], C1[13]); w.w = pk2(C1[14], C1[15]); pb[3] = __builtin_bit_cast(bf16x8, w); }
;     if (HASNEXT) {
;         constexpr int VPER = (DK == 64) ? 6 : 4;
; #pragma unroll
;         for (int g = 0; g < 2 * A::NDS; ++g) { __builtin_amdgcn_sched_group_barrier(0x008, 1, 0); __builtin_amdgcn_sched_group_barrier(0x002, VPER, 0); }
;     }
;     asm volatile("" : "+v"(l));
;     __builtin_amdgcn_sched_barrier(0);
; #pragma unroll
.LBB0_779:
	s_setprio 1
	s_mov_b32 s11, 0x23a30000
	ds_read_b64_tr_b16 v[110:111], v96 offset:26624
	v_mfma_f32_32x32x16_bf16 v[48:63], v[216:219], v[76:79], 0
	v_lshl_add_u64 v[126:127], v[122:123], 0, s[8:9]
	v_add_co_u32_e32 v32, vcc, s11, v126
	v_lshl_add_u64 v[128:129], v[124:125], 0, s[8:9]
	s_nop 0
	v_addc_co_u32_e32 v33, vcc, 0, v127, vcc
	s_mov_b32 s11, 0x24aa8000
	global_load_dwordx4 v[88:91], v[32:33], off
	v_add_co_u32_e32 v32, vcc, s11, v128
	ds_read_b64_tr_b16 v[112:113], v96 offset:28160
	s_nop 0
	v_addc_co_u32_e32 v33, vcc, 0, v129, vcc
	global_load_dwordx4 v[92:95], v[32:33], off
	v_mfma_f32_32x32x16_bf16 v[32:47], v[220:223], v[76:79], 0
	v_add_f32_e32 v150, v146, v172
	v_add_f32_e32 v150, v132, v150
	v_add_f32_e32 v150, v148, v150
	v_add_f32_e32 v150, v133, v150
	v_add_f32_e32 v150, v158, v150
	v_add_f32_e32 v150, v134, v150
	ds_read_b64_tr_b16 v[106:107], v96 offset:26688
	v_mfma_f32_32x32x16_bf16 v[32:47], v[224:227], v[72:75], v[32:47]
	v_add_f32_e32 v150, v159, v150
	v_add_f32_e32 v150, v135, v150
	v_add_f32_e32 v150, v160, v150
	v_add_f32_e32 v150, v136, v150
	v_add_f32_e32 v150, v162, v150
	v_add_f32_e32 v150, v137, v150
	ds_read_b64_tr_b16 v[108:109], v96 offset:28224
	v_mfma_f32_32x32x16_bf16 v[48:63], v[228:231], v[72:75], v[48:63]
	s_waitcnt vmcnt(3)
	ds_write_b128 v130, v[80:83] offset:13312
	s_waitcnt vmcnt(2)
	ds_write_b128 v117, v[84:87] offset:38912
	v_add_f32_e32 v150, v164, v150
	v_add_f32_e32 v150, v139, v150
	v_add_f32_e32 v150, v166, v150
	v_add_f32_e32 v150, v141, v150
	v_add_f32_e32 v150, v161, v150
	v_add_f32_e32 v150, v138, v150
	ds_read_b64_tr_b16 v[102:103], v96 offset:29696
	v_mfma_f32_32x32x16_bf16 v[32:47], v[236:239], v[68:71], v[32:47]
	v_add_f32_e32 v150, v163, v150
	v_add_f32_e32 v150, v140, v150
	v_add_f32_e32 v150, v165, v150
	v_add_f32_e32 v150, v142, v150
	v_add_f32_e32 v150, v168, v150
	v_add_f32_e32 v150, v143, v150
	ds_read_b64_tr_b16 v[104:105], v96 offset:31232
	v_mfma_f32_32x32x16_bf16 v[48:63], v[240:243], v[68:71], v[48:63]
	v_add_f32_e32 v150, v167, v150
	v_add_f32_e32 v150, v144, v150
	v_add_f32_e32 v150, v169, v150
	v_add_f32_e32 v150, v145, v150
	ds_read_b64_tr_b16 v[98:99], v96 offset:29760
	ds_read_b64_tr_b16 v[100:101], v96 offset:31296
	v_add_f32_e32 v150, v170, v150
	v_add_f32_e32 v150, v147, v150
	v_mfma_f32_32x32x16_bf16 v[32:47], v[244:247], v[64:67], v[32:47]
	v_add_f32_e32 v150, v171, v150
	v_add_f32_e32 v152, v149, v150
	v_cvt_pk_bf16_f32 v182, v146, v148
	v_cvt_pk_bf16_f32 v183, v158, v159
	v_cvt_pk_bf16_f32 v184, v160, v162
	v_cvt_pk_bf16_f32 v185, v164, v166
	v_mfma_f32_32x32x16_bf16 v[48:63], v[248:251], v[64:67], v[48:63]
	v_cvt_pk_bf16_f32 v158, v161, v163
	v_cvt_pk_bf16_f32 v159, v165, v168
	v_cvt_pk_bf16_f32 v160, v167, v169
	v_cvt_pk_bf16_f32 v161, v170, v171
	v_cvt_pk_bf16_f32 v132, v132, v133
	v_cvt_pk_bf16_f32 v133, v134, v135
	v_cvt_pk_bf16_f32 v134, v136, v137
	v_cvt_pk_bf16_f32 v135, v139, v141
	v_cvt_pk_bf16_f32 v136, v138, v140
	v_cvt_pk_bf16_f32 v137, v142, v143
	v_cvt_pk_bf16_f32 v138, v144, v145
	v_cvt_pk_bf16_f32 v139, v147, v149
	s_waitcnt lgkmcnt(8)
	v_mfma_f32_32x32x16_bf16 v[16:31], v[110:113], v[182:185], v[16:31]
	ds_read_b64_tr_b16 v[110:111], v96 offset:32832
	ds_read_b64_tr_b16 v[112:113], v96 offset:34368
	ds_read_b64_tr_b16 v[140:141], v96 offset:35904
	ds_read_b64_tr_b16 v[142:143], v96 offset:37440
	v_exp_f32_e32 v162, v51
	v_exp_f32_e32 v163, v36
	v_exp_f32_e32 v164, v52
	s_waitcnt lgkmcnt(10)
	v_mfma_f32_32x32x16_bf16 v[0:15], v[106:109], v[182:185], v[0:15]
	ds_read_b64_tr_b16 v[106:107], v96 offset:32768
	ds_read_b64_tr_b16 v[108:109], v96 offset:34304
	v_exp_f32_e32 v165, v37
	v_exp_f32_e32 v166, v53
	v_exp_f32_e32 v167, v38
	v_exp_f32_e32 v168, v54
	v_exp_f32_e32 v169, v39
	s_waitcnt lgkmcnt(8)
	v_mfma_f32_32x32x16_bf16 v[16:31], v[102:105], v[158:161], v[16:31]
	ds_read_b64_tr_b16 v[102:103], v96 offset:35840
	ds_read_b64_tr_b16 v[104:105], v96 offset:37376
	ds_read_b128 v[216:219], v131 offset:4608
	ds_read_b128 v[220:223], v131
	v_exp_f32_e32 v170, v55
	v_exp_f32_e32 v171, v40
	v_exp_f32_e32 v153, v32
	v_exp_f32_e32 v154, v48
	s_waitcnt lgkmcnt(10)
	v_mfma_f32_32x32x16_bf16 v[0:15], v[98:101], v[158:161], v[0:15]
	ds_read_b128 v[224:227], v131 offset:32
	ds_read_b128 v[228:231], v131 offset:64
	v_exp_f32_e32 v155, v33
	v_exp_f32_e32 v158, v49
	v_exp_f32_e32 v159, v34
	v_exp_f32_e32 v160, v50
	s_waitcnt lgkmcnt(6)
	v_mfma_f32_32x32x16_bf16 v[16:31], v[106:109], v[132:135], v[16:31]
	ds_read_b128 v[236:239], v131 offset:96
	ds_read_b128 v[240:243], v131 offset:4640
	v_exp_f32_e32 v161, v35
	v_exp_f32_e32 v173, v56
	v_exp_f32_e32 v180, v41
	v_exp_f32_e32 v181, v57
	v_mfma_f32_32x32x16_bf16 v[0:15], v[110:113], v[132:135], v[0:15]
	ds_read_b128 v[244:247], v131 offset:4672
	ds_read_b128 v[248:251], v131 offset:4704
	v_exp_f32_e32 v182, v42
	v_exp_f32_e32 v183, v58
	v_exp_f32_e32 v184, v43
	v_exp_f32_e32 v185, v59
	s_waitcnt lgkmcnt(8)
	v_mfma_f32_32x32x16_bf16 v[16:31], v[102:105], v[136:139], v[16:31]
	v_exp_f32_e32 v186, v44
	v_exp_f32_e32 v187, v60
	v_exp_f32_e32 v188, v45
	v_exp_f32_e32 v189, v61
	v_mfma_f32_32x32x16_bf16 v[0:15], v[140:143], v[136:139], v[0:15]
	v_exp_f32_e32 v190, v46
	v_exp_f32_e32 v191, v62
	v_exp_f32_e32 v192, v47
	v_exp_f32_e32 v193, v63
	s_setprio 0
	s_waitcnt lgkmcnt(0)
	s_barrier
; template <int DK, int PAR, bool HASNEXT, bool LDK, bool LDV, bool STK> ...
;     ...
; #pragma unroll
;         for (int ds = 0; ds < A::NDS; ++ds) {
;             kf[ds][0] = *(const LAS bf16x8*)(Kb + aoffk + ds * 32);
;             kf[ds][1] = *(const LAS bf16x8*)(Kb + aoffk + 32 * A::KSTR + ds * 32);
;         }
;     }
;     s16x4 vlo[4][2], vhi[4][2];
; #pragma unroll
;     for (int j = 0; j < 2; ++j) {
;         vlo[j][0] = vtr(Vb + aoffv + j * 16 * A::VSTR); vhi[j][0] = vtr(Vb + aoffv + (j * 16 + 8) * A::VSTR);
;         vlo[j][1] = vtr(Vb + aoffv + j * 16 * A::VSTR + 64); vhi[j][1] = vtr(Vb + aoffv + (j * 16 + 8) * A::VSTR + 64);
;     }
;     if (HASNEXT) {
;         f32x16 z;
; #pragma unroll
;         for (int i = 0; i < 16; ++i) z[i] = 0.f;
; #pragma unroll
;         for (int ds = 0; ds < A::NDS; ++ds) {
;             N0 = __builtin_amdgcn_mfma_f32_32x32x16_bf16(kf[ds][0], qf[ds], ds == 0 ? z : N0, 0, 0, 0);
;             N1 = __builtin_amdgcn_mfma_f32_32x32x16_bf16(kf[ds][1], qf[ds], ds == 0 ? z : N1, 0, 0, 0);
;         }
;     }
; #pragma unroll
;     for (int i = 0; i < 16; ++i) { l += C0[i]; l += C1[i]; }
;     bf16x8 pb[4];
;     { u32x4 w;
;       w.x = pk2(C0[0], C0[1]); w.y = pk2(C0[2], C0[3]); w.z = pk2(C0[4], C0[5]); w.w = pk2(C0[6], C0[7]); pb[0] = __builtin_bit_cast(bf16x8, w);
;       w.x = pk2(C0[8], C0[9]); w.y = pk2(C0[10], C0[11]); w.z = pk2(C0[12], C0[13]); w.w = pk2(C0[14], C0[15]); pb[1] = __builtin_bit_cast(bf16x8, w);
;       w.x = pk2(C1[0], C1[1]); w.y = pk2(C1[2], C1[3]); w.z = pk2(C1[4], C1[5]); w.w = pk2(C1[6], C1[7]); pb[2] = __builtin_bit_cast(bf16x8, w);
;       w.x = pk2(C1[8], C1[9]); w.y = pk2(C1[10], C1[11]); w.z = pk2(C1[12], C1[13]); w.w = pk2(C1[14], C1[15]); pb[3] = __builtin_bit_cast(bf16x8, w); }
;     if (HASNEXT) {
;         constexpr int VPER = (DK == 64) ? 6 : 4;
; #pragma unroll
;         for (int g = 0; g < 2 * A::NDS; ++g) { __builtin_amdgcn_sched_group_barrier(0x008, 1, 0); __builtin_amdgcn_sched_group_barrier(0x002, VPER, 0); }
;     }
;     asm volatile("" : "+v"(l));
;     __builtin_amdgcn_sched_barrier(0);
; #pragma unroll
;     for (int j = 2; j < 4; ++j) {
;         vlo[j][0] = vtr(Vb + aoffv + j * 16 * A::VSTR); vhi[j][0] = vtr(Vb + aoffv + (j * 16 + 8) * A::VSTR);
;         vlo[j][1] = vtr(Vb + aoffv + j * 16 * A::VSTR + 64); vhi[j][1] = vtr(Vb + aoffv + (j * 16 + 8) * A::VSTR + 64);
;     }
	s_setprio 1
	s_mov_b32 s11, 0x23a34000
	ds_read_b64_tr_b16 v[110:111], v96 offset:38912
	ds_read_b64_tr_b16 v[112:113], v96 offset:40448
	v_mfma_f32_32x32x16_bf16 v[48:63], v[216:219], v[76:79], 0
	v_add_co_u32_e32 v32, vcc, s11, v126
	s_mov_b32 s11, 0x24aac000
	s_nop 0
	v_addc_co_u32_e32 v33, vcc, 0, v127, vcc
	global_load_dwordx4 v[80:83], v[32:33], off
	v_add_co_u32_e32 v32, vcc, s11, v128
	ds_read_b64_tr_b16 v[106:107], v96 offset:38976
	s_nop 0
	v_addc_co_u32_e32 v33, vcc, 0, v129, vcc
	global_load_dwordx4 v[84:87], v[32:33], off
	v_mfma_f32_32x32x16_bf16 v[32:47], v[220:223], v[76:79], 0
	ds_read_b64_tr_b16 v[108:109], v96 offset:40512
	ds_read_b64_tr_b16 v[102:103], v96 offset:41984
	ds_read_b64_tr_b16 v[104:105], v96 offset:43520
	ds_read_b64_tr_b16 v[98:99], v96 offset:42048
	ds_read_b64_tr_b16 v[100:101], v96 offset:43584
	v_add_f32_e32 v126, v153, v152
	v_add_f32_e32 v126, v154, v126
	v_add_f32_e32 v126, v155, v126
	v_add_f32_e32 v126, v158, v126
	v_add_f32_e32 v126, v159, v126
	v_mfma_f32_32x32x16_bf16 v[32:47], v[224:227], v[72:75], v[32:47]
	v_add_f32_e32 v126, v160, v126
	v_add_f32_e32 v126, v161, v126
	v_add_f32_e32 v126, v162, v126
	v_add_f32_e32 v126, v163, v126
	v_add_f32_e32 v126, v164, v126
	v_mfma_f32_32x32x16_bf16 v[32:47], v[228:231], v[68:71], v[32:47]
	s_waitcnt vmcnt(3)
	ds_write_b128 v130, v[88:91]
	s_waitcnt vmcnt(2)
	ds_write_b128 v117, v[92:95] offset:26624
	v_add_f32_e32 v126, v165, v126
	v_add_f32_e32 v126, v166, v126
	v_add_f32_e32 v126, v167, v126
	v_add_f32_e32 v126, v168, v126
	v_add_f32_e32 v126, v169, v126
	v_mfma_f32_32x32x16_bf16 v[32:47], v[236:239], v[64:67], v[32:47]
	v_add_f32_e32 v126, v170, v126
	v_add_f32_e32 v126, v171, v126
	v_add_f32_e32 v126, v173, v126
	v_add_f32_e32 v126, v180, v126
	v_cvt_pk_bf16_f32 v144, v164, v166
	v_cvt_pk_bf16_f32 v145, v168, v170
	v_cvt_pk_bf16_f32 v136, v186, v188
	v_cvt_pk_bf16_f32 v137, v190, v192
	v_mfma_f32_32x32x16_bf16 v[48:63], v[240:243], v[72:75], v[48:63]
	v_add_f32_e32 v126, v181, v126
	v_add_f32_e32 v126, v182, v126
	v_add_f32_e32 v126, v183, v126
	v_add_f32_e32 v126, v184, v126
	v_cvt_pk_bf16_f32 v134, v171, v180
	v_cvt_pk_bf16_f32 v135, v182, v184
	v_mfma_f32_32x32x16_bf16 v[48:63], v[244:247], v[68:71], v[48:63]
	v_add_f32_e32 v126, v185, v126
	v_add_f32_e32 v126, v186, v126
	v_add_f32_e32 v126, v187, v126
	v_add_f32_e32 v126, v188, v126
	v_cvt_pk_bf16_f32 v142, v154, v158
	v_cvt_pk_bf16_f32 v143, v160, v162
	v_mfma_f32_32x32x16_bf16 v[48:63], v[248:251], v[64:67], v[48:63]
	v_add_f32_e32 v126, v189, v126
	v_add_f32_e32 v126, v190, v126
	v_add_f32_e32 v126, v191, v126
	v_add_f32_e32 v126, v192, v126
	v_add_f32_e32 v172, v193, v126
	v_cvt_pk_bf16_f32 v126, v153, v155
	v_cvt_pk_bf16_f32 v127, v159, v161
	v_cvt_pk_bf16_f32 v128, v163, v165
	v_cvt_pk_bf16_f32 v129, v167, v169
	v_cvt_pk_bf16_f32 v182, v173, v181
	v_cvt_pk_bf16_f32 v183, v183, v185
	v_cvt_pk_bf16_f32 v184, v187, v189
	v_cvt_pk_bf16_f32 v185, v191, v193
	s_waitcnt lgkmcnt(8)
	v_mfma_f32_32x32x16_bf16 v[16:31], v[110:113], v[126:129], v[16:31]
	ds_read_b64_tr_b16 v[110:111], v96 offset:45120
	ds_read_b64_tr_b16 v[112:113], v96 offset:46656
	v_exp_f32_e32 v146, v32
	v_exp_f32_e32 v132, v48
	v_exp_f32_e32 v148, v33
	v_exp_f32_e32 v133, v49
	v_exp_f32_e32 v158, v34
	s_waitcnt lgkmcnt(8)
	v_mfma_f32_32x32x16_bf16 v[0:15], v[106:109], v[126:129], v[0:15]
	ds_read_b64_tr_b16 v[106:107], v96 offset:45056
	ds_read_b64_tr_b16 v[108:109], v96 offset:46592
	ds_read_b64_tr_b16 v[126:127], v96 offset:48192
	ds_read_b64_tr_b16 v[128:129], v96 offset:49728
	v_exp_f32_e32 v159, v35
	v_exp_f32_e32 v160, v36
	v_exp_f32_e32 v162, v37
	s_waitcnt lgkmcnt(10)
	v_mfma_f32_32x32x16_bf16 v[16:31], v[102:105], v[134:137], v[16:31]
	ds_read_b64_tr_b16 v[102:103], v96 offset:48128
	ds_read_b64_tr_b16 v[104:105], v96 offset:49664
	ds_read_b128 v[216:219], v131 offset:17920
	ds_read_b128 v[220:223], v131 offset:13312
	v_exp_f32_e32 v164, v38
	v_exp_f32_e32 v139, v54
	v_exp_f32_e32 v166, v39
	v_exp_f32_e32 v141, v55
	s_waitcnt lgkmcnt(12)
	v_mfma_f32_32x32x16_bf16 v[0:15], v[98:101], v[134:137], v[0:15]
	ds_read_b128 v[224:227], v131 offset:13344
	ds_read_b128 v[228:231], v131 offset:17952
	v_exp_f32_e32 v161, v40
	v_exp_f32_e32 v134, v50
	v_exp_f32_e32 v135, v51
	v_exp_f32_e32 v136, v52
	s_waitcnt lgkmcnt(8)
	v_mfma_f32_32x32x16_bf16 v[16:31], v[106:109], v[142:145], v[16:31]
	ds_read_b128 v[236:239], v131 offset:13376
	ds_read_b128 v[240:243], v131 offset:17984
	v_exp_f32_e32 v137, v53
	v_exp_f32_e32 v138, v56
	v_exp_f32_e32 v163, v41
	v_exp_f32_e32 v140, v57
	v_mfma_f32_32x32x16_bf16 v[0:15], v[110:113], v[142:145], v[0:15]
	ds_read_b128 v[244:247], v131 offset:13408
	ds_read_b128 v[248:251], v131 offset:18016
	v_exp_f32_e32 v165, v42
	v_exp_f32_e32 v168, v43
	v_exp_f32_e32 v167, v44
	v_exp_f32_e32 v169, v45
	s_waitcnt lgkmcnt(8)
	v_mfma_f32_32x32x16_bf16 v[16:31], v[102:105], v[182:185], v[16:31]
	v_exp_f32_e32 v170, v46
	v_exp_f32_e32 v147, v62
	v_exp_f32_e32 v171, v47
	v_exp_f32_e32 v142, v58
	v_mfma_f32_32x32x16_bf16 v[0:15], v[126:129], v[182:185], v[0:15]
	v_exp_f32_e32 v143, v59
	v_exp_f32_e32 v144, v60
	v_exp_f32_e32 v145, v61
	v_exp_f32_e32 v149, v63
	s_setprio 0
	s_waitcnt lgkmcnt(0)
	s_barrier
	s_add_i32 s10, s10, 2
	v_lshl_add_u64 v[122:123], v[122:123], 0, s[34:35]
	s_cmpk_lt_u32 s10, 0x7e
	v_lshl_add_u64 v[124:125], v[124:125], 0, s[34:35]
	s_cbranch_scc1 .LBB0_779
; template <int DK, int PAR, bool HASNEXT, bool LDK, bool LDV, bool STK> ...
;     ...
;     if (LDK) { ldk0 = *(const u32x4*)(kg0 + (size_t)(t + 3) * kstep); if (has1) ldk1 = *(const u32x4*)(kg1 + (size_t)(t + 3) * kstep); }
;     if (LDV) ldv = *(const u32x4*)(vg + (size_t)(t + 2) * vstep);
;     bf16x8 kf[A::NDS][2];
;     if (HASNEXT) {
; #pragma unroll
;         for (int ds = 0; ds < A::NDS; ++ds) {
;             kf[ds][0] = *(const LAS bf16x8*)(Kb + aoffk + ds * 32);
;             kf[ds][1] = *(const LAS bf16x8*)(Kb + aoffk + 32 * A::KSTR + ds * 32);
;         }
;     }
;     s16x4 vlo[4][2], vhi[4][2];
; #pragma unroll
;     for (int j = 0; j < 2; ++j) {
;         vlo[j][0] = vtr(Vb + aoffv + j * 16 * A::VSTR); vhi[j][0] = vtr(Vb + aoffv + (j * 16 + 8) * A::VSTR);
;         vlo[j][1] = vtr(Vb + aoffv + j * 16 * A::VSTR + 64); vhi[j][1] = vtr(Vb + aoffv + (j * 16 + 8) * A::VSTR + 64);
;     }
;     if (HASNEXT) {
;         f32x16 z;
; #pragma unroll
;         for (int i = 0; i < 16; ++i) z[i] = 0.f;
; #pragma unroll
;         for (int ds = 0; ds < A::NDS; ++ds) {
;             N0 = __builtin_amdgcn_mfma_f32_32x32x16_bf16(kf[ds][0], qf[ds], ds == 0 ? z : N0, 0, 0, 0);
;             N1 = __builtin_amdgcn_mfma_f32_32x32x16_bf16(kf[ds][1], qf[ds], ds == 0 ? z : N1, 0, 0, 0);
;         }
;     }
; #pragma unroll
;     for (int i = 0; i < 16; ++i) { l += C0[i]; l += C1[i]; }
;     bf16x8 pb[4];
;     { u32x4 w;
;       w.x = pk2(C0[0], C0[1]); w.y = pk2(C0[2], C0[3]); w.z = pk2(C0[4], C0[5]); w.w = pk2(C0[6], C0[7]); pb[0] = __builtin_bit_cast(bf16x8, w);
;       w.x = pk2(C0[8], C0[9]); w.y = pk2(C0[10], C0[11]); w.z = pk2(C0[12], C0[13]); w.w = pk2(C0[14], C0[15]); pb[1] = __builtin_bit_cast(bf16x8, w);
;       w.x = pk2(C1[0], C1[1]); w.y = pk2(C1[2], C1[3]); w.z = pk2(C1[4], C1[5]); w.w = pk2(C1[6], C1[7]); pb[2] = __builtin_bit_cast(bf16x8, w);
;       w.x = pk2(C1[8], C1[9]); w.y = pk2(C1[10], C1[11]); w.z = pk2(C1[12], C1[13]); w.w = pk2(C1[14], C1[15]); pb[3] = __builtin_bit_cast(bf16x8, w); }
;     if (HASNEXT) {
;         constexpr int VPER = (DK == 64) ? 6 : 4;
; #pragma unroll
;         for (int g = 0; g < 2 * A::NDS; ++g) { __builtin_amdgcn_sched_group_barrier(0x008, 1, 0); __builtin_amdgcn_sched_group_barrier(0x002, VPER, 0); }
;     }
;     asm volatile("" : "+v"(l));
;     __builtin_amdgcn_sched_barrier(0);
; #pragma unroll
	s_waitcnt vmcnt(0)
	ds_read_b128 v[80:83], v130
	s_waitcnt lgkmcnt(0)
	s_setprio 1
	ds_read_b128 v[48:51], v131 offset:17920
	ds_read_b128 v[124:127], v131 offset:17952
	ds_read_b128 v[182:185], v131 offset:13376
	ds_read_b128 v[186:189], v131 offset:17984
	ds_read_b128 v[190:193], v131 offset:13408
	ds_read_b128 v[194:197], v131 offset:18016
	ds_read_b64_tr_b16 v[110:111], v96 offset:26624
	ds_read_b64_tr_b16 v[112:113], v96 offset:28160
	ds_read_b64_tr_b16 v[106:107], v96 offset:26688
	s_waitcnt lgkmcnt(8)
	v_mfma_f32_32x32x16_bf16 v[48:63], v[48:51], v[76:79], 0
	v_add_co_u32_e32 v32, vcc, 0x20c000, v120
	ds_read_b64_tr_b16 v[108:109], v96 offset:28224
	s_nop 0
	v_addc_co_u32_e32 v33, vcc, 0, v121, vcc
	global_load_dwordx4 v[88:91], v[32:33], off
	v_add_co_u32_e32 v32, vcc, 0x208000, v118
	ds_read_b128 v[120:123], v131 offset:13344
	s_nop 0
	v_addc_co_u32_e32 v33, vcc, 0, v119, vcc
	global_load_dwordx4 v[92:95], v[32:33], off
	ds_read_b128 v[32:35], v131 offset:13312
	s_waitcnt lgkmcnt(0)
	v_mfma_f32_32x32x16_bf16 v[32:47], v[32:35], v[76:79], 0
	ds_read_b64_tr_b16 v[102:103], v96 offset:29696
	ds_read_b64_tr_b16 v[104:105], v96 offset:31232
	ds_read_b64_tr_b16 v[98:99], v96 offset:29760
	ds_read_b64_tr_b16 v[100:101], v96 offset:31296
	v_mfma_f32_32x32x16_bf16 v[32:47], v[120:123], v[72:75], v[32:47]
	v_add_f32_e32 v120, v146, v172
	v_add_f32_e32 v120, v132, v120
	v_cvt_pk_bf16_f32 v132, v132, v133
	v_add_f32_e32 v120, v148, v120
	v_add_f32_e32 v120, v133, v120
	v_cvt_pk_bf16_f32 v133, v134, v135
	v_add_f32_e32 v120, v158, v120
	v_add_f32_e32 v120, v134, v120
	v_cvt_pk_bf16_f32 v134, v136, v137
	v_add_f32_e32 v120, v159, v120
	v_add_f32_e32 v120, v135, v120
	v_cvt_pk_bf16_f32 v135, v139, v141
	v_mfma_f32_32x32x16_bf16 v[48:63], v[124:127], v[72:75], v[48:63]
	v_cvt_pk_bf16_f32 v124, v161, v163
	v_cvt_pk_bf16_f32 v125, v165, v168
	v_cvt_pk_bf16_f32 v126, v167, v169
	v_cvt_pk_bf16_f32 v127, v170, v171
	v_add_f32_e32 v120, v160, v120
	v_add_f32_e32 v120, v136, v120
	v_add_f32_e32 v120, v162, v120
	v_add_f32_e32 v120, v137, v120
	v_mfma_f32_32x32x16_bf16 v[32:47], v[182:185], v[68:71], v[32:47]
	v_add_f32_e32 v120, v164, v120
	v_add_f32_e32 v120, v139, v120
	v_add_f32_e32 v120, v166, v120
	v_add_f32_e32 v120, v141, v120
	v_add_f32_e32 v120, v161, v120
	v_add_f32_e32 v120, v138, v120
	v_cvt_pk_bf16_f32 v136, v138, v140
	v_mfma_f32_32x32x16_bf16 v[48:63], v[186:189], v[68:71], v[48:63]
	v_add_f32_e32 v120, v163, v120
	v_add_f32_e32 v120, v140, v120
	v_add_f32_e32 v120, v165, v120
	v_add_f32_e32 v120, v142, v120
	v_add_f32_e32 v120, v168, v120
	v_add_f32_e32 v120, v143, v120
	v_cvt_pk_bf16_f32 v137, v142, v143
	v_mfma_f32_32x32x16_bf16 v[32:47], v[190:193], v[64:67], v[32:47]
	v_add_f32_e32 v120, v167, v120
	v_add_f32_e32 v120, v144, v120
	v_add_f32_e32 v120, v169, v120
	v_add_f32_e32 v120, v145, v120
	v_add_f32_e32 v120, v170, v120
	v_add_f32_e32 v120, v147, v120
	v_cvt_pk_bf16_f32 v138, v144, v145
	v_mfma_f32_32x32x16_bf16 v[48:63], v[194:197], v[64:67], v[48:63]
	v_add_f32_e32 v120, v171, v120
	v_add_f32_e32 v128, v149, v120
	v_cvt_pk_bf16_f32 v120, v146, v148
	v_cvt_pk_bf16_f32 v121, v158, v159
	v_cvt_pk_bf16_f32 v122, v160, v162
	v_cvt_pk_bf16_f32 v123, v164, v166
	v_cvt_pk_bf16_f32 v139, v147, v149
	s_nop 0
	v_mfma_f32_32x32x16_bf16 v[16:31], v[110:113], v[120:123], v[16:31]
	ds_read_b64_tr_b16 v[110:111], v96 offset:32832
	ds_read_b64_tr_b16 v[112:113], v96 offset:34368
	v_exp_f32_e32 v140, v32
	v_exp_f32_e32 v141, v48
	v_exp_f32_e32 v142, v33
	v_exp_f32_e32 v143, v49
	v_exp_f32_e32 v144, v34
	v_mfma_f32_32x32x16_bf16 v[0:15], v[106:109], v[120:123], v[0:15]
	ds_read_b64_tr_b16 v[106:107], v96 offset:32768
	ds_read_b64_tr_b16 v[108:109], v96 offset:34304
	ds_read_b64_tr_b16 v[120:121], v96 offset:35904
	ds_read_b64_tr_b16 v[122:123], v96 offset:37440
	v_exp_f32_e32 v145, v50
	v_exp_f32_e32 v146, v35
	v_exp_f32_e32 v147, v51
	s_waitcnt lgkmcnt(8)
	v_mfma_f32_32x32x16_bf16 v[16:31], v[102:105], v[124:127], v[16:31]
	ds_read_b64_tr_b16 v[102:103], v96 offset:35840
	ds_read_b64_tr_b16 v[104:105], v96 offset:37376
	v_exp_f32_e32 v148, v36
	v_exp_f32_e32 v149, v52
	v_exp_f32_e32 v150, v37
	v_exp_f32_e32 v151, v53
	v_exp_f32_e32 v152, v38
	s_waitcnt lgkmcnt(8)
	v_mfma_f32_32x32x16_bf16 v[0:15], v[98:101], v[124:127], v[0:15]
	v_exp_f32_e32 v153, v54
	v_exp_f32_e32 v154, v39
	v_exp_f32_e32 v155, v55
	v_exp_f32_e32 v158, v40
	v_exp_f32_e32 v159, v58
	v_exp_f32_e32 v160, v43
	v_exp_f32_e32 v161, v59
	s_waitcnt lgkmcnt(4)
	v_mfma_f32_32x32x16_bf16 v[16:31], v[106:109], v[132:135], v[16:31]
	v_exp_f32_e32 v162, v44
	v_exp_f32_e32 v163, v60
	v_exp_f32_e32 v164, v45
	v_exp_f32_e32 v165, v61
	v_exp_f32_e32 v166, v46
	v_exp_f32_e32 v167, v62
	v_exp_f32_e32 v168, v47
	v_mfma_f32_32x32x16_bf16 v[0:15], v[110:113], v[132:135], v[0:15]
	v_exp_f32_e32 v132, v56
	v_exp_f32_e32 v133, v41
	v_exp_f32_e32 v134, v57
	v_exp_f32_e32 v135, v42
	v_exp_f32_e32 v169, v63
	s_waitcnt lgkmcnt(0)
	v_mfma_f32_32x32x16_bf16 v[16:31], v[102:105], v[136:139], v[16:31]
	v_mfma_f32_32x32x16_bf16 v[0:15], v[120:123], v[136:139], v[0:15]
	s_setprio 0
	s_waitcnt vmcnt(3)
	ds_write_b128 v130, v[80:83]
	s_waitcnt vmcnt(2)
	ds_write_b128 v117, v[84:87] offset:38912
	s_waitcnt lgkmcnt(0)
	s_barrier
; template <int DK, int PAR, bool HASNEXT, bool LDK, bool LDV, bool STK> ...
;     ...
;     if (LDK) { ldk0 = *(const u32x4*)(kg0 + (size_t)(t + 3) * kstep); if (has1) ldk1 = *(const u32x4*)(kg1 + (size_t)(t + 3) * kstep); }
;     if (LDV) ldv = *(const u32x4*)(vg + (size_t)(t + 2) * vstep);
;     bf16x8 kf[A::NDS][2];
;     if (HASNEXT) {
; #pragma unroll
;         for (int ds = 0; ds < A::NDS; ++ds) {
;             kf[ds][0] = *(const LAS bf16x8*)(Kb + aoffk + ds * 32);
;             kf[ds][1] = *(const LAS bf16x8*)(Kb + aoffk + 32 * A::KSTR + ds * 32);
;         }
;     }
;     s16x4 vlo[4][2], vhi[4][2];
; #pragma unroll
;     for (int j = 0; j < 2; ++j) {
;         vlo[j][0] = vtr(Vb + aoffv + j * 16 * A::VSTR); vhi[j][0] = vtr(Vb + aoffv + (j * 16 + 8) * A::VSTR);
;         vlo[j][1] = vtr(Vb + aoffv + j * 16 * A::VSTR + 64); vhi[j][1] = vtr(Vb + aoffv + (j * 16 + 8) * A::VSTR + 64);
;     }
;     if (HASNEXT) {
;         f32x16 z;
; #pragma unroll
;         for (int i = 0; i < 16; ++i) z[i] = 0.f;
; #pragma unroll
;         for (int ds = 0; ds < A::NDS; ++ds) {
;             N0 = __builtin_amdgcn_mfma_f32_32x32x16_bf16(kf[ds][0], qf[ds], ds == 0 ? z : N0, 0, 0, 0);
;             N1 = __builtin_amdgcn_mfma_f32_32x32x16_bf16(kf[ds][1], qf[ds], ds == 0 ? z : N1, 0, 0, 0);
;         }
;     }
; #pragma unroll
;     for (int i = 0; i < 16; ++i) { l += C0[i]; l += C1[i]; }
;     bf16x8 pb[4];
;     { u32x4 w;
;       w.x = pk2(C0[0], C0[1]); w.y = pk2(C0[2], C0[3]); w.z = pk2(C0[4], C0[5]); w.w = pk2(C0[6], C0[7]); pb[0] = __builtin_bit_cast(bf16x8, w);
;       w.x = pk2(C0[8], C0[9]); w.y = pk2(C0[10], C0[11]); w.z = pk2(C0[12], C0[13]); w.w = pk2(C0[14], C0[15]); pb[1] = __builtin_bit_cast(bf16x8, w);
;       w.x = pk2(C1[0], C1[1]); w.y = pk2(C1[2], C1[3]); w.z = pk2(C1[4], C1[5]); w.w = pk2(C1[6], C1[7]); pb[2] = __builtin_bit_cast(bf16x8, w);
;       w.x = pk2(C1[8], C1[9]); w.y = pk2(C1[10], C1[11]); w.z = pk2(C1[12], C1[13]); w.w = pk2(C1[14], C1[15]); pb[3] = __builtin_bit_cast(bf16x8, w); }
;     if (HASNEXT) {
;         constexpr int VPER = (DK == 64) ? 6 : 4;
; #pragma unroll
;         for (int g = 0; g < 2 * A::NDS; ++g) { __builtin_amdgcn_sched_group_barrier(0x008, 1, 0); __builtin_amdgcn_sched_group_barrier(0x002, VPER, 0); }
;     }
;     asm volatile("" : "+v"(l));
;     __builtin_amdgcn_sched_barrier(0);
; #pragma unroll
	s_setprio 1
	ds_read_b128 v[32:35], v131
	s_mov_b32 s8, 0x20c000
	ds_read_b128 v[84:87], v131 offset:32
	ds_read_b128 v[98:101], v131 offset:4640
	ds_read_b128 v[102:105], v131 offset:64
	ds_read_b128 v[106:109], v131 offset:4672
	ds_read_b128 v[110:113], v131 offset:96
	ds_read_b64_tr_b16 v[122:123], v96 offset:38912
	ds_read_b64_tr_b16 v[124:125], v96 offset:40448
	s_waitcnt lgkmcnt(7)
	v_mfma_f32_32x32x16_bf16 v[32:47], v[32:35], v[76:79], 0
	v_add_co_u32_e32 v48, vcc, s8, v118
	v_add_f32_e32 v52, v140, v128
	s_nop 0
	v_addc_co_u32_e32 v49, vcc, 0, v119, vcc
	global_load_dwordx4 v[80:83], v[48:49], off
	ds_read_b128 v[48:51], v131 offset:4608
	v_add_f32_e32 v52, v141, v52
	v_add_f32_e32 v52, v142, v52
	v_add_f32_e32 v128, v143, v52
	s_waitcnt lgkmcnt(0)
	v_mfma_f32_32x32x16_bf16 v[48:63], v[48:51], v[76:79], 0
	v_add_f32_e32 v128, v144, v128
	v_add_f32_e32 v128, v145, v128
	v_add_f32_e32 v128, v146, v128
	v_add_f32_e32 v128, v147, v128
	v_add_f32_e32 v128, v148, v128
	v_add_f32_e32 v136, v149, v128
	ds_read_b128 v[118:121], v131 offset:4704
	v_mfma_f32_32x32x16_bf16 v[32:47], v[84:87], v[72:75], v[32:47]
	v_add_f32_e32 v84, v150, v136
	v_add_f32_e32 v84, v151, v84
	v_add_f32_e32 v84, v152, v84
	v_add_f32_e32 v84, v153, v84
	v_add_f32_e32 v84, v154, v84
	v_add_f32_e32 v86, v155, v84
	ds_read_b64_tr_b16 v[126:127], v96 offset:38976
	v_mfma_f32_32x32x16_bf16 v[48:63], v[98:101], v[72:75], v[48:63]
	v_add_f32_e32 v86, v158, v86
	v_add_f32_e32 v86, v132, v86
	v_add_f32_e32 v86, v133, v86
	v_add_f32_e32 v86, v134, v86
	v_add_f32_e32 v86, v135, v86
	v_add_f32_e32 v98, v159, v86
	ds_read_b64_tr_b16 v[128:129], v96 offset:40512
	v_mfma_f32_32x32x16_bf16 v[32:47], v[102:105], v[68:71], v[32:47]
	v_add_f32_e32 v98, v160, v98
	v_add_f32_e32 v98, v161, v98
	v_add_f32_e32 v98, v162, v98
	v_add_f32_e32 v98, v163, v98
	v_add_f32_e32 v98, v164, v98
	v_add_f32_e32 v100, v165, v98
	ds_read_b64_tr_b16 v[84:85], v96 offset:41984
	v_mfma_f32_32x32x16_bf16 v[48:63], v[106:109], v[68:71], v[48:63]
	v_add_f32_e32 v100, v166, v100
	v_add_f32_e32 v100, v167, v100
	v_add_f32_e32 v100, v168, v100
	ds_read_b64_tr_b16 v[86:87], v96 offset:43520
	ds_read_b64_tr_b16 v[98:99], v96 offset:42048
	v_add_f32_e32 v136, v169, v100
	ds_read_b64_tr_b16 v[100:101], v96 offset:43584
	v_cvt_pk_bf16_f32 v102, v140, v142
	v_cvt_pk_bf16_f32 v103, v144, v146
	v_mfma_f32_32x32x16_bf16 v[32:47], v[110:113], v[64:67], v[32:47]
	v_cvt_pk_bf16_f32 v104, v148, v150
	v_cvt_pk_bf16_f32 v105, v152, v154
	v_cvt_pk_bf16_f32 v106, v158, v133
	v_cvt_pk_bf16_f32 v107, v135, v160
	v_cvt_pk_bf16_f32 v108, v162, v164
	v_cvt_pk_bf16_f32 v109, v166, v168
	s_waitcnt lgkmcnt(6)
	v_mfma_f32_32x32x16_bf16 v[48:63], v[118:121], v[64:67], v[48:63]
	v_cvt_pk_bf16_f32 v110, v141, v143
	v_cvt_pk_bf16_f32 v111, v145, v147
	v_cvt_pk_bf16_f32 v112, v149, v151
	v_cvt_pk_bf16_f32 v113, v153, v155
	v_cvt_pk_bf16_f32 v118, v132, v134
	v_cvt_pk_bf16_f32 v119, v159, v161
	v_cvt_pk_bf16_f32 v120, v163, v165
	v_cvt_pk_bf16_f32 v121, v167, v169
	v_mfma_f32_32x32x16_bf16 v[16:31], v[122:125], v[102:105], v[16:31]
	ds_read_b64_tr_b16 v[122:123], v96 offset:45120
	ds_read_b64_tr_b16 v[124:125], v96 offset:46656
	v_exp_f32_e32 v132, v32
	v_exp_f32_e32 v133, v48
	v_exp_f32_e32 v134, v33
	v_exp_f32_e32 v135, v49
	v_exp_f32_e32 v137, v34
	s_waitcnt lgkmcnt(6)
	v_mfma_f32_32x32x16_bf16 v[0:15], v[126:129], v[102:105], v[0:15]
	ds_read_b64_tr_b16 v[102:103], v96 offset:45056
	ds_read_b64_tr_b16 v[104:105], v96 offset:46592
	ds_read_b64_tr_b16 v[126:127], v96 offset:48192
	ds_read_b64_tr_b16 v[128:129], v96 offset:49728
	v_exp_f32_e32 v138, v50
	v_exp_f32_e32 v139, v35
	v_exp_f32_e32 v140, v51
	s_waitcnt lgkmcnt(8)
	v_mfma_f32_32x32x16_bf16 v[16:31], v[84:87], v[106:109], v[16:31]
	ds_read_b64_tr_b16 v[84:85], v96 offset:48128
	ds_read_b64_tr_b16 v[86:87], v96 offset:49664
	v_exp_f32_e32 v141, v36
	v_exp_f32_e32 v142, v52
	v_exp_f32_e32 v143, v37
	v_exp_f32_e32 v144, v53
	v_exp_f32_e32 v145, v38
	s_waitcnt lgkmcnt(8)
	v_mfma_f32_32x32x16_bf16 v[0:15], v[98:101], v[106:109], v[0:15]
	v_exp_f32_e32 v146, v54
	v_exp_f32_e32 v147, v39
	v_exp_f32_e32 v148, v55
	v_exp_f32_e32 v149, v40
	v_exp_f32_e32 v150, v58
	v_exp_f32_e32 v151, v43
	v_exp_f32_e32 v152, v59
	s_waitcnt lgkmcnt(4)
	v_mfma_f32_32x32x16_bf16 v[16:31], v[102:105], v[110:113], v[16:31]
	v_exp_f32_e32 v153, v44
	v_exp_f32_e32 v154, v60
	v_exp_f32_e32 v155, v45
	v_exp_f32_e32 v158, v61
	v_exp_f32_e32 v159, v46
	v_exp_f32_e32 v160, v62
	v_exp_f32_e32 v161, v47
	v_mfma_f32_32x32x16_bf16 v[0:15], v[122:125], v[110:113], v[0:15]
	v_exp_f32_e32 v122, v56
	v_exp_f32_e32 v123, v41
	v_exp_f32_e32 v124, v57
	v_exp_f32_e32 v125, v42
	v_exp_f32_e32 v162, v63
	s_waitcnt lgkmcnt(0)
	v_mfma_f32_32x32x16_bf16 v[16:31], v[84:87], v[118:121], v[16:31]
	v_mfma_f32_32x32x16_bf16 v[0:15], v[126:129], v[118:121], v[0:15]
	s_setprio 0
	s_waitcnt vmcnt(2)
	ds_write_b128 v130, v[88:91] offset:13312
	s_waitcnt vmcnt(1)
	ds_write_b128 v117, v[92:95] offset:26624
	s_waitcnt lgkmcnt(0)
	s_barrier
; template <int DK, int PAR, bool HASNEXT, bool LDK, bool LDV, bool STK> ...
;     ...
;             kf[ds][0] = *(const LAS bf16x8*)(Kb + aoffk + ds * 32);
;             kf[ds][1] = *(const LAS bf16x8*)(Kb + aoffk + 32 * A::KSTR + ds * 32);
;         }
;     }
;     s16x4 vlo[4][2], vhi[4][2];
; #pragma unroll
;     for (int j = 0; j < 2; ++j) {
;         vlo[j][0] = vtr(Vb + aoffv + j * 16 * A::VSTR); vhi[j][0] = vtr(Vb + aoffv + (j * 16 + 8) * A::VSTR);
;         vlo[j][1] = vtr(Vb + aoffv + j * 16 * A::VSTR + 64); vhi[j][1] = vtr(Vb + aoffv + (j * 16 + 8) * A::VSTR + 64);
;     }
;     if (HASNEXT) {
;         f32x16 z;
; #pragma unroll
;         for (int i = 0; i < 16; ++i) z[i] = 0.f;
; #pragma unroll
;         for (int ds = 0; ds < A::NDS; ++ds) {
;             N0 = __builtin_amdgcn_mfma_f32_32x32x16_bf16(kf[ds][0], qf[ds], ds == 0 ? z : N0, 0, 0, 0);
;             N1 = __builtin_amdgcn_mfma_f32_32x32x16_bf16(kf[ds][1], qf[ds], ds == 0 ? z : N1, 0, 0, 0);
;         }
;     }
; #pragma unroll
;     for (int i = 0; i < 16; ++i) { l += C0[i]; l += C1[i]; }
;     bf16x8 pb[4];
;     { u32x4 w;
;       w.x = pk2(C0[0], C0[1]); w.y = pk2(C0[2], C0[3]); w.z = pk2(C0[4], C0[5]); w.w = pk2(C0[6], C0[7]); pb[0] = __builtin_bit_cast(bf16x8, w);
;       w.x = pk2(C0[8], C0[9]); w.y = pk2(C0[10], C0[11]); w.z = pk2(C0[12], C0[13]); w.w = pk2(C0[14], C0[15]); pb[1] = __builtin_bit_cast(bf16x8, w);
;       w.x = pk2(C1[0], C1[1]); w.y = pk2(C1[2], C1[3]); w.z = pk2(C1[4], C1[5]); w.w = pk2(C1[6], C1[7]); pb[2] = __builtin_bit_cast(bf16x8, w);
;       w.x = pk2(C1[8], C1[9]); w.y = pk2(C1[10], C1[11]); w.z = pk2(C1[12], C1[13]); w.w = pk2(C1[14], C1[15]); pb[3] = __builtin_bit_cast(bf16x8, w); }
;     if (HASNEXT) {
;         constexpr int VPER = (DK == 64) ? 6 : 4;
; #pragma unroll
;         for (int g = 0; g < 2 * A::NDS; ++g) { __builtin_amdgcn_sched_group_barrier(0x008, 1, 0); __builtin_amdgcn_sched_group_barrier(0x002, VPER, 0); }
;     }
;     asm volatile("" : "+v"(l));
;     __builtin_amdgcn_sched_barrier(0);
; #pragma unroll
;     for (int j = 2; j < 4; ++j) {
;         vlo[j][0] = vtr(Vb + aoffv + j * 16 * A::VSTR); vhi[j][0] = vtr(Vb + aoffv + (j * 16 + 8) * A::VSTR);
;         vlo[j][1] = vtr(Vb + aoffv + j * 16 * A::VSTR + 64); vhi[j][1] = vtr(Vb + aoffv + (j * 16 + 8) * A::VSTR + 64);
;     }
; #pragma unroll
;     for (int j = 0; j < 4; ++j) {
	s_setprio 1
	ds_read_b128 v[32:35], v131 offset:13312
	ds_read_b128 v[48:51], v131 offset:17920
	ds_read_b128 v[84:87], v131 offset:13344
	ds_read_b128 v[88:91], v131 offset:17952
	ds_read_b128 v[92:95], v131 offset:13376
	ds_read_b128 v[98:101], v131 offset:17984
	ds_read_b128 v[102:105], v131 offset:13408
	ds_read_b128 v[106:109], v131 offset:18016
	ds_read_b64_tr_b16 v[110:111], v96 offset:26624
	s_waitcnt lgkmcnt(8)
	v_mfma_f32_32x32x16_bf16 v[32:47], v[32:35], v[76:79], 0
	v_add_f32_e32 v52, v132, v136
	v_add_f32_e32 v52, v133, v52
	v_add_f32_e32 v52, v134, v52
	v_add_f32_e32 v52, v135, v52
	v_add_f32_e32 v52, v137, v52
	v_add_f32_e32 v118, v138, v52
	ds_read_b64_tr_b16 v[112:113], v96 offset:28160
	s_waitcnt lgkmcnt(8)
	v_mfma_f32_32x32x16_bf16 v[48:63], v[48:51], v[76:79], 0
	v_add_f32_e32 v78, v139, v118
	v_add_f32_e32 v78, v140, v78
	v_add_f32_e32 v78, v141, v78
	v_add_f32_e32 v78, v142, v78
	v_add_f32_e32 v78, v143, v78
	v_add_f32_e32 v118, v144, v78
	ds_read_b64_tr_b16 v[76:77], v96 offset:26688
	s_waitcnt lgkmcnt(8)
	v_mfma_f32_32x32x16_bf16 v[32:47], v[84:87], v[72:75], v[32:47]
	v_add_f32_e32 v84, v145, v118
	v_add_f32_e32 v84, v146, v84
	v_add_f32_e32 v84, v147, v84
	v_add_f32_e32 v84, v148, v84
	v_add_f32_e32 v84, v149, v84
	v_add_f32_e32 v84, v122, v84
	ds_read_b64_tr_b16 v[78:79], v96 offset:28224
	s_waitcnt lgkmcnt(8)
	v_mfma_f32_32x32x16_bf16 v[48:63], v[88:91], v[72:75], v[48:63]
	v_add_f32_e32 v74, v123, v84
	v_add_f32_e32 v74, v124, v74
	v_add_f32_e32 v74, v125, v74
	v_add_f32_e32 v74, v150, v74
	v_add_f32_e32 v74, v151, v74
	v_add_f32_e32 v84, v152, v74
	ds_read_b64_tr_b16 v[72:73], v96 offset:29696
	s_waitcnt lgkmcnt(8)
	v_mfma_f32_32x32x16_bf16 v[32:47], v[92:95], v[68:71], v[32:47]
	v_add_f32_e32 v84, v153, v84
	v_add_f32_e32 v84, v154, v84
	v_add_f32_e32 v84, v155, v84
	v_add_f32_e32 v84, v158, v84
	v_add_f32_e32 v84, v159, v84
	v_add_f32_e32 v84, v160, v84
	ds_read_b64_tr_b16 v[74:75], v96 offset:31232
	s_waitcnt lgkmcnt(8)
	v_mfma_f32_32x32x16_bf16 v[48:63], v[98:101], v[68:71], v[48:63]
	v_add_f32_e32 v70, v161, v84
	ds_read_b64_tr_b16 v[68:69], v96 offset:29760
	v_add_f32_e32 v118, v162, v70
	ds_read_b64_tr_b16 v[70:71], v96 offset:31296
	v_cvt_pk_bf16_f32 v84, v132, v134
	v_cvt_pk_bf16_f32 v85, v137, v139
	v_cvt_pk_bf16_f32 v86, v141, v143
	v_cvt_pk_bf16_f32 v87, v145, v147
	s_waitcnt lgkmcnt(9)
	v_mfma_f32_32x32x16_bf16 v[32:47], v[102:105], v[64:67], v[32:47]
	v_cvt_pk_bf16_f32 v88, v149, v123
	v_cvt_pk_bf16_f32 v89, v125, v151
	v_cvt_pk_bf16_f32 v90, v153, v155
	v_cvt_pk_bf16_f32 v91, v159, v161
	v_cvt_pk_bf16_f32 v92, v133, v135
	v_cvt_pk_bf16_f32 v93, v138, v140
	s_waitcnt lgkmcnt(8)
	v_mfma_f32_32x32x16_bf16 v[48:63], v[106:109], v[64:67], v[48:63]
	v_cvt_pk_bf16_f32 v94, v142, v144
	v_cvt_pk_bf16_f32 v95, v146, v148
	v_cvt_pk_bf16_f32 v64, v122, v124
	v_cvt_pk_bf16_f32 v65, v150, v152
	v_cvt_pk_bf16_f32 v66, v154, v158
	v_cvt_pk_bf16_f32 v67, v160, v162
	s_waitcnt lgkmcnt(6)
	v_mfma_f32_32x32x16_bf16 v[16:31], v[110:113], v[84:87], v[16:31]
	ds_read_b64_tr_b16 v[98:99], v96 offset:35904
	ds_read_b64_tr_b16 v[100:101], v96 offset:37440
	v_exp_f32_e32 v102, v32
	s_nop 0
	v_exp_f32_e32 v103, v48
	v_exp_f32_e32 v48, v33
	v_exp_f32_e32 v63, v63
	s_waitcnt lgkmcnt(6)
	v_mfma_f32_32x32x16_bf16 v[0:15], v[76:79], v[84:87], v[0:15]
	ds_read_b64_tr_b16 v[76:77], v96 offset:32768
	ds_read_b64_tr_b16 v[78:79], v96 offset:34304
	ds_read_b64_tr_b16 v[84:85], v96 offset:32832
	ds_read_b64_tr_b16 v[86:87], v96 offset:34368
	s_waitcnt lgkmcnt(8)
	v_mfma_f32_32x32x16_bf16 v[16:31], v[72:75], v[88:91], v[16:31]
	ds_read_b64_tr_b16 v[72:73], v96 offset:35840
	ds_read_b64_tr_b16 v[74:75], v96 offset:37376
	s_waitcnt lgkmcnt(8)
	v_mfma_f32_32x32x16_bf16 v[0:15], v[68:71], v[88:91], v[0:15]
	v_exp_f32_e32 v68, v49
	v_exp_f32_e32 v49, v34
	v_exp_f32_e32 v69, v50
	v_exp_f32_e32 v50, v35
	v_exp_f32_e32 v70, v51
	v_exp_f32_e32 v51, v36
	v_exp_f32_e32 v71, v52
	s_waitcnt lgkmcnt(4)
	v_mfma_f32_32x32x16_bf16 v[16:31], v[76:79], v[92:95], v[16:31]
	v_exp_f32_e32 v52, v37
	v_exp_f32_e32 v76, v53
	v_exp_f32_e32 v53, v38
	v_exp_f32_e32 v77, v54
	v_exp_f32_e32 v54, v39
	v_exp_f32_e32 v78, v55
	v_exp_f32_e32 v55, v40
	s_waitcnt lgkmcnt(2)
	v_mfma_f32_32x32x16_bf16 v[0:15], v[84:87], v[92:95], v[0:15]
	v_exp_f32_e32 v79, v56
	v_exp_f32_e32 v56, v41
	v_exp_f32_e32 v84, v57
	v_exp_f32_e32 v57, v42
	v_exp_f32_e32 v85, v58
	v_exp_f32_e32 v58, v43
	v_exp_f32_e32 v86, v59
	s_waitcnt lgkmcnt(0)
	v_mfma_f32_32x32x16_bf16 v[16:31], v[72:75], v[64:67], v[16:31]
	v_exp_f32_e32 v59, v44
	v_exp_f32_e32 v72, v60
	v_exp_f32_e32 v60, v45
	v_exp_f32_e32 v73, v61
	v_exp_f32_e32 v61, v46
	v_exp_f32_e32 v74, v62
	v_exp_f32_e32 v62, v47
	v_mfma_f32_32x32x16_bf16 v[0:15], v[98:101], v[64:67], v[0:15]
	s_setprio 0
	s_waitcnt vmcnt(0)
	ds_write_b128 v117, v[80:83] offset:38912
	s_waitcnt lgkmcnt(0)
	s_barrier
; template <int DK, int PAR, bool HASNEXT, bool LDK, bool LDV, bool STK> ...
;     ...
; #pragma unroll
;     for (int i = 0; i < 16; ++i) { l += C0[i]; l += C1[i]; }
;     bf16x8 pb[4];
;     { u32x4 w;
;       w.x = pk2(C0[0], C0[1]); w.y = pk2(C0[2], C0[3]); w.z = pk2(C0[4], C0[5]); w.w = pk2(C0[6], C0[7]); pb[0] = __builtin_bit_cast(bf16x8, w);
;       w.x = pk2(C0[8], C0[9]); w.y = pk2(C0[10], C0[11]); w.z = pk2(C0[12], C0[13]); w.w = pk2(C0[14], C0[15]); pb[1] = __builtin_bit_cast(bf16x8, w);
;       w.x = pk2(C1[0], C1[1]); w.y = pk2(C1[2], C1[3]); w.z = pk2(C1[4], C1[5]); w.w = pk2(C1[6], C1[7]); pb[2] = __builtin_bit_cast(bf16x8, w);
;       w.x = pk2(C1[8], C1[9]); w.y = pk2(C1[10], C1[11]); w.z = pk2(C1[12], C1[13]); w.w = pk2(C1[14], C1[15]); pb[3] = __builtin_bit_cast(bf16x8, w); }
;     if (HASNEXT) {
;         constexpr int VPER = (DK == 64) ? 6 : 4;
; #pragma unroll
;         for (int g = 0; g < 2 * A::NDS; ++g) { __builtin_amdgcn_sched_group_barrier(0x008, 1, 0); __builtin_amdgcn_sched_group_barrier(0x002, VPER, 0); }
;     }
;     asm volatile("" : "+v"(l));
;     __builtin_amdgcn_sched_barrier(0);
; #pragma unroll
;     for (int j = 2; j < 4; ++j) {
;         vlo[j][0] = vtr(Vb + aoffv + j * 16 * A::VSTR); vhi[j][0] = vtr(Vb + aoffv + (j * 16 + 8) * A::VSTR);
;         vlo[j][1] = vtr(Vb + aoffv + j * 16 * A::VSTR + 64); vhi[j][1] = vtr(Vb + aoffv + (j * 16 + 8) * A::VSTR + 64);
;     }
; #pragma unroll
;     for (int j = 0; j < 4; ++j) {
;         const bf16x8 a0 = __builtin_shufflevector(vlo[j][0], vhi[j][0], 0, 1, 2, 3, 4, 5, 6, 7);
;         const bf16x8 a1 = __builtin_shufflevector(vlo[j][1], vhi[j][1], 0, 1, 2, 3, 4, 5, 6, 7);
;         o0 = __builtin_amdgcn_mfma_f32_32x32x16_bf16(a0, pb[j], o0, 0, 0, 0);
;         o1 = __builtin_amdgcn_mfma_f32_32x32x16_bf16(a1, pb[j], o1, 0, 0, 0);
;     }
;     if (HASNEXT) {
; #pragma unroll
;         for (int i = 0; i < 16; ++i) { N0[i] = __builtin_amdgcn_exp2f(N0[i]); N1[i] = __builtin_amdgcn_exp2f(N1[i]); }
; #pragma unroll
;         for (int g = 0; g < 8; ++g) { __builtin_amdgcn_sched_group_barrier(0x008, 1, 0); __builtin_amdgcn_sched_group_barrier(0x002, 4, 0); }
;     }
;     __builtin_amdgcn_sched_barrier(0);
;     __builtin_amdgcn_s_setprio(0);
;     if (STK) { LAS unsigned char* Kn = lds + PAR * A::KBUF; *(LAS u32x4*)(Kn + kl0) = stk0; if (has1) *(LAS u32x4*)(Kn + kl1) = stk1; }
	s_setprio 1
	v_add_f32_e32 v64, v102, v118
	v_add_f32_e32 v64, v103, v64
	v_add_f32_e32 v64, v48, v64
	v_add_f32_e32 v64, v68, v64
	v_add_f32_e32 v64, v49, v64
	v_add_f32_e32 v64, v69, v64
	v_add_f32_e32 v64, v50, v64
	v_add_f32_e32 v64, v70, v64
	v_add_f32_e32 v64, v51, v64
	v_add_f32_e32 v64, v71, v64
	v_add_f32_e32 v64, v52, v64
	v_add_f32_e32 v64, v76, v64
	v_add_f32_e32 v64, v53, v64
	v_add_f32_e32 v64, v77, v64
	v_add_f32_e32 v64, v54, v64
	v_add_f32_e32 v64, v78, v64
	v_add_f32_e32 v64, v55, v64
	v_add_f32_e32 v64, v79, v64
	v_add_f32_e32 v64, v56, v64
	v_add_f32_e32 v64, v84, v64
	v_add_f32_e32 v64, v57, v64
	v_add_f32_e32 v64, v85, v64
	v_add_f32_e32 v64, v58, v64
	v_add_f32_e32 v64, v86, v64
	v_add_f32_e32 v64, v59, v64
	v_add_f32_e32 v64, v72, v64
	v_add_f32_e32 v64, v60, v64
	v_add_f32_e32 v64, v73, v64
	ds_read_b64_tr_b16 v[32:33], v96 offset:38912
	ds_read_b64_tr_b16 v[34:35], v96 offset:40448
	ds_read_b64_tr_b16 v[38:39], v96 offset:40512
	ds_read_b64_tr_b16 v[36:37], v96 offset:38976
	ds_read_b64_tr_b16 v[40:41], v96 offset:41984
	ds_read_b64_tr_b16 v[42:43], v96 offset:43520
	ds_read_b64_tr_b16 v[46:47], v96 offset:43584
	ds_read_b64_tr_b16 v[44:45], v96 offset:42048
	v_add_f32_e32 v64, v61, v64
	v_add_f32_e32 v64, v74, v64
	v_add_f32_e32 v64, v62, v64
	v_add_f32_e32 v64, v63, v64
	v_cvt_pk_bf16_f32 v48, v102, v48
	v_cvt_pk_bf16_f32 v49, v49, v50
	v_cvt_pk_bf16_f32 v50, v51, v52
	v_cvt_pk_bf16_f32 v51, v53, v54
	v_cvt_pk_bf16_f32 v52, v55, v56
	v_cvt_pk_bf16_f32 v53, v57, v58
	v_cvt_pk_bf16_f32 v54, v59, v60
	v_cvt_pk_bf16_f32 v55, v61, v62
	v_cvt_pk_bf16_f32 v56, v103, v68
	v_cvt_pk_bf16_f32 v57, v69, v70
	v_cvt_pk_bf16_f32 v58, v71, v76
	v_cvt_pk_bf16_f32 v59, v77, v78
	v_cvt_pk_bf16_f32 v60, v79, v84
	v_cvt_pk_bf16_f32 v61, v85, v86
	v_cvt_pk_bf16_f32 v62, v72, v73
	v_cvt_pk_bf16_f32 v63, v74, v63
	s_waitcnt lgkmcnt(6)
	v_mfma_f32_32x32x16_bf16 v[16:31], v[32:35], v[48:51], v[16:31]
	ds_read_b64_tr_b16 v[32:33], v96 offset:45056
	ds_read_b64_tr_b16 v[34:35], v96 offset:46592
	s_waitcnt lgkmcnt(6)
	v_mfma_f32_32x32x16_bf16 v[0:15], v[36:39], v[48:51], v[0:15]
	ds_read_b64_tr_b16 v[38:39], v96 offset:46656
	ds_read_b64_tr_b16 v[36:37], v96 offset:45120
	s_waitcnt lgkmcnt(6)
	v_mfma_f32_32x32x16_bf16 v[16:31], v[40:43], v[52:55], v[16:31]
	s_waitcnt lgkmcnt(4)
	v_mfma_f32_32x32x16_bf16 v[0:15], v[44:47], v[52:55], v[0:15]
	s_waitcnt lgkmcnt(2)
	v_mfma_f32_32x32x16_bf16 v[16:31], v[32:35], v[56:59], v[16:31]
	ds_read_b64_tr_b16 v[32:33], v96 offset:48128
	ds_read_b64_tr_b16 v[34:35], v96 offset:49664
	s_waitcnt lgkmcnt(2)
	v_mfma_f32_32x32x16_bf16 v[0:15], v[36:39], v[56:59], v[0:15]
	ds_read_b64_tr_b16 v[38:39], v96 offset:49728
	ds_read_b64_tr_b16 v[36:37], v96 offset:48192
	s_waitcnt lgkmcnt(2)
	v_mfma_f32_32x32x16_bf16 v[16:31], v[32:35], v[60:63], v[16:31]
	s_waitcnt lgkmcnt(0)
	v_mfma_f32_32x32x16_bf16 v[0:15], v[36:39], v[60:63], v[0:15]
	s_setprio 0
	v_mov_b32_e32 v32, v64
	s_nop 1
	v_permlane32_swap_b32_e32 v64, v32
	v_add_f32_e32 v32, v64, v32
	v_div_scale_f32 v33, s[8:9], v32, v32, 1.0
	v_rcp_f32_e32 v34, v33
	v_lshlrev_b32_e32 v96, 1, v116
	s_waitcnt lgkmcnt(0)
	s_barrier
	v_fma_f32 v35, -v33, v34, 1.0
	v_fmac_f32_e32 v34, v35, v34
	v_div_scale_f32 v35, vcc, 1.0, v32, 1.0
	v_mul_f32_e32 v36, v35, v34
	v_fma_f32 v37, -v33, v36, v35
	v_fmac_f32_e32 v36, v37, v34
	v_fma_f32 v33, -v33, v36, v35
	v_div_fmas_f32 v33, v33, v34, v36
	v_div_fixup_f32 v32, v33, v32, 1.0
	v_pk_mul_f32 v[16:17], v[16:17], v[32:33] op_sel_hi:[1,0]
	v_pk_mul_f32 v[18:19], v[18:19], v[32:33] op_sel_hi:[1,0]
	v_pk_mul_f32 v[0:1], v[0:1], v[32:33] op_sel_hi:[1,0]
	v_pk_mul_f32 v[2:3], v[2:3], v[32:33] op_sel_hi:[1,0]
	v_lshlrev_b64 v[34:35], 11, v[114:115]
	v_cvt_pk_bf16_f32 v16, v16, v17
	v_cvt_pk_bf16_f32 v17, v18, v19
	v_pk_mul_f32 v[18:19], v[20:21], v[32:33] op_sel_hi:[1,0]
	v_pk_mul_f32 v[20:21], v[22:23], v[32:33] op_sel_hi:[1,0]
	v_cvt_pk_bf16_f32 v0, v0, v1
	v_cvt_pk_bf16_f32 v1, v2, v3
	v_pk_mul_f32 v[2:3], v[4:5], v[32:33] op_sel_hi:[1,0]
	v_pk_mul_f32 v[4:5], v[6:7], v[32:33] op_sel_hi:[1,0]
	v_lshl_add_u64 v[34:35], s[6:7], 0, v[34:35]
	v_cvt_pk_bf16_f32 v18, v18, v19
	v_cvt_pk_bf16_f32 v19, v20, v21
	v_cvt_pk_bf16_f32 v2, v2, v3
	v_cvt_pk_bf16_f32 v3, v4, v5
	v_lshl_add_u64 v[34:35], v[34:35], 0, v[96:97]
	v_permlane32_swap_b32_e32 v16, v18
	v_permlane32_swap_b32_e32 v17, v19
	v_permlane32_swap_b32_e32 v0, v2
	v_permlane32_swap_b32_e32 v1, v3
	global_store_dwordx4 v[34:35], v[16:19], off
	global_store_dwordx4 v[34:35], v[0:3], off offset:64
	v_pk_mul_f32 v[20:21], v[30:31], v[32:33] op_sel_hi:[1,0]
	v_pk_mul_f32 v[16:17], v[24:25], v[32:33] op_sel_hi:[1,0]
	v_pk_mul_f32 v[18:19], v[26:27], v[32:33] op_sel_hi:[1,0]
	v_pk_mul_f32 v[0:1], v[8:9], v[32:33] op_sel_hi:[1,0]
	v_pk_mul_f32 v[2:3], v[10:11], v[32:33] op_sel_hi:[1,0]
	v_cvt_pk_bf16_f32 v16, v16, v17
	v_cvt_pk_bf16_f32 v17, v18, v19
	v_pk_mul_f32 v[18:19], v[28:29], v[32:33] op_sel_hi:[1,0]
	v_cvt_pk_bf16_f32 v0, v0, v1
	v_cvt_pk_bf16_f32 v1, v2, v3
	v_pk_mul_f32 v[2:3], v[12:13], v[32:33] op_sel_hi:[1,0]
	v_pk_mul_f32 v[4:5], v[14:15], v[32:33] op_sel_hi:[1,0]
	v_cvt_pk_bf16_f32 v18, v18, v19
	v_cvt_pk_bf16_f32 v19, v20, v21
	v_cvt_pk_bf16_f32 v2, v2, v3
	v_cvt_pk_bf16_f32 v3, v4, v5
	v_permlane32_swap_b32_e32 v16, v18
	v_permlane32_swap_b32_e32 v17, v19
	v_permlane32_swap_b32_e32 v0, v2
	v_permlane32_swap_b32_e32 v1, v3
	global_store_dwordx4 v[34:35], v[16:19], off offset:32
	global_store_dwordx4 v[34:35], v[0:3], off offset:96
	s_branch .LBB0_740
